# first chunk of each prep workgroup is published on the regular path (next chunk's step 1b) instead of at once: no store round trip on the critical chain
# baseline (speedup 1.0000x reference)
.LBB0_239:
	s_lshl_b32 s6, s53, 12
	v_lshlrev_b32_e32 v1, 3, v1
	s_add_i32 s6, s6, 0
	s_add_i32 s7, s6, 0x10000
	v_and_b32_e32 v1, 56, v1
	v_lshlrev_b32_e32 v89, 7, v94
	v_xor_b32_e32 v90, v88, v1
	v_xor_b32_e32 v91, v18, v1
	v_add_u32_e32 v89, s7, v89
	v_mul_u32_u24_e32 v1, 0x90, v96
	v_lshl_add_u32 v1, v88, 1, v1
	v_add_u32_e32 v1, s49, v1
	v_lshl_add_u32 v88, v90, 1, v89
	v_xor_b32_e32 v18, 32, v90
	v_xor_b32_e32 v90, 48, v90
	v_lshl_add_u32 v91, v91, 1, v89
	v_lshl_add_u32 v90, v90, 1, v89
	v_lshl_add_u32 v89, v18, 1, v89
	s_waitcnt lgkmcnt(0)
	s_barrier
	ds_read_b128 v[18:21], v1
	ds_read_b128 v[22:25], v88
	ds_read_b128 v[26:29], v88 offset:16384
	ds_read_b128 v[30:33], v1 offset:9216
	ds_read_b128 v[122:125], v1 offset:32
	ds_read_b128 v[126:129], v91
	s_add_i32 s7, s51, 0xe000
	s_mov_b64 s[40:41], 0
	s_waitcnt lgkmcnt(4)
	v_mfma_f32_32x32x16_bf16 v[2:17], v[18:21], v[22:25], 0
	ds_read_b128 v[18:21], v91 offset:16384
	ds_read_b128 v[22:25], v1 offset:9248
	s_waitcnt lgkmcnt(4)
	v_mfma_f32_32x32x16_bf16 v[106:121], v[26:29], v[30:33], 0
	ds_read_b128 v[26:29], v1 offset:64
	ds_read_b128 v[30:33], v89
	s_waitcnt lgkmcnt(4)
	v_mfma_f32_32x32x16_bf16 v[2:17], v[122:125], v[126:129], v[2:17]
	ds_read_b128 v[122:125], v89 offset:16384
	ds_read_b128 v[126:129], v1 offset:9280
	s_waitcnt lgkmcnt(4)
	v_mfma_f32_32x32x16_bf16 v[106:121], v[18:21], v[22:25], v[106:121]
	ds_read_b128 v[18:21], v1 offset:96
	ds_read_b128 v[22:25], v90
	s_waitcnt lgkmcnt(4)
	v_mfma_f32_32x32x16_bf16 v[2:17], v[26:29], v[30:33], v[2:17]
	ds_read_b128 v[26:29], v90 offset:16384
	ds_read_b128 v[30:33], v1 offset:9312
	s_waitcnt lgkmcnt(4)
	v_mfma_f32_32x32x16_bf16 v[106:121], v[122:125], v[126:129], v[106:121]
	s_waitcnt lgkmcnt(2)
	v_mfma_f32_32x32x16_bf16 v[2:17], v[18:21], v[22:25], v[2:17]
	s_waitcnt lgkmcnt(0)
	v_mfma_f32_32x32x16_bf16 v[106:121], v[26:29], v[30:33], v[106:121]
	v_or_b32_e32 v1, s34, v92
	v_lshlrev_b32_e32 v1, 1, v1
	v_add_u32_e32 v88, s7, v1
	s_add_i32 s7, s51, 0xe400
	v_add_u32_e32 v89, s7, v1
	s_lshl_b32 s7, s48, 9
	s_and_b32 s7, s7, 0x7ffffc00
	s_lshl_b32 s6, s52, 12
	s_add_i32 s6, s6, s7
	v_or_b32_e32 v1, s6, v92
	v_lshlrev_b32_e32 v1, 1, v1
	v_readlane_b32 s6, v250, 18
	s_nop 1
	v_cvt_pk_bf16_f32 v18, v2, v3
	v_cvt_pk_bf16_f32 v19, v4, v5
	v_cvt_pk_bf16_f32 v20, v6, v7
	v_cvt_pk_bf16_f32 v21, v8, v9
	buffer_store_dwordx4 v[18:21], v88, s[72:75], 0 offen sc1
	v_cvt_pk_bf16_f32 v22, v10, v11
	v_cvt_pk_bf16_f32 v23, v12, v13
	v_cvt_pk_bf16_f32 v24, v14, v15
	v_cvt_pk_bf16_f32 v25, v16, v17
	buffer_store_dwordx4 v[22:25], v89, s[72:75], 0 offen sc1
	v_add_u32_e32 v90, s51, v1
	s_addk_i32 s51, 0x400
	v_add_u32_e32 v91, s51, v1
	v_cvt_pk_bf16_f32 v26, v106, v107
	v_cvt_pk_bf16_f32 v27, v108, v109
	v_cvt_pk_bf16_f32 v28, v110, v111
	v_cvt_pk_bf16_f32 v29, v112, v113
	s_cmp_lg_u32 s50, s50
	buffer_store_dwordx4 v[26:29], v90, s[72:75], 0 offen sc1
	v_cvt_pk_bf16_f32 v30, v114, v115
	v_cvt_pk_bf16_f32 v31, v116, v117
	v_cvt_pk_bf16_f32 v32, v118, v119
	v_cvt_pk_bf16_f32 v33, v120, v121
	s_cselect_b64 s[28:29], -1, 0
	s_cmp_eq_u32 s50, s50
	buffer_store_dwordx4 v[30:33], v91, s[72:75], 0 offen sc1
	s_cbranch_scc1 .LBB0_241
	s_waitcnt vmcnt(0)
	s_and_b64 s[40:41], s[54:55], exec
